# HGRN2 read-out (group-norm x gate) loop: both halves of each row requested up front (6 loads in flight, one round trip per row instead of two)
# speedup vs baseline: 1.0090x; 1.0013x over previous
; __device__ __forceinline__ float bf2f(bf16_t v) { return __uint_as_float((unsigned)v << 16); }
; __device__ __forceinline__ u32x4 pack8(const float* v) { u32x4 w; w.x = cvt_pk_bf16(v[0], v[1]); w.y = cvt_pk_bf16(v[2], v[3]); w.z = cvt_pk_bf16(v[4], v[5]); w.w = cvt_pk_bf16(v[6], v[7]); return w; }
; __global__ void __launch_bounds__(512) mk_fwd(Params P) {
;     ...
;             for (int row = gw; row < M; row += NGW) {
; #pragma unroll
;                 for (int hh = 0; hh < 4; ++hh) { const size_t off = (size_t)row * 2048 + hh * 512 + lane * 8;
;                     const bf16x8 a = __builtin_nontemporal_load((const bf16x8*)(OF + off)), b = __builtin_nontemporal_load((const bf16x8*)(OB + off)), gt = *(const bf16x8*)(Gb + off);
;                     float o[8]; float s = 0.f;
; #pragma unroll
;                     for (int e = 0; e < 8; ++e) { o[e] = bf2f((bf16_t)a[e]) + bf2f((bf16_t)b[e]); s += o[e] * o[e]; }
;                     const float rinv = rsqrtf(wave_sum(s) * (1.f / 512.f) + EPS);
; #pragma unroll
;                     for (int e = 0; e < 8; ++e) o[e] = o[e] * rinv * bf2f((bf16_t)gt[e]);
;                     *(u32x4*)(Gb + off) = pack8(o); }
.LBB0_63:
	s_nop 0
	v_add_co_u32_e32 v2, vcc, 0xfbbff400, v0
	s_mov_b32 s6, 0xfbbff800
	s_nop 0
	v_addc_co_u32_e32 v3, vcc, -1, v1, vcc
	flat_load_dwordx4 v[16:19], v[2:3] nt
	v_add_co_u32_e32 v2, vcc, 0xfffff400, v0
	s_add_i32 s3, s3, s42
	s_nop 0
	v_addc_co_u32_e32 v3, vcc, -1, v1, vcc
	v_add_co_u32_e32 v4, vcc, 0xf77ff400, v0
	flat_load_dwordx4 v[20:23], v[2:3] nt
	s_nop 0
	v_addc_co_u32_e32 v5, vcc, -1, v1, vcc
	flat_load_dwordx4 v[30:33], v[4:5]
	v_add_co_u32_e32 v66, vcc, 0xfbbff800, v0
	s_nop 1
	v_addc_co_u32_e32 v67, vcc, -1, v1, vcc
	flat_load_dwordx4 v[62:65], v[66:67] nt
	v_add_co_u32_e32 v34, vcc, 0xfffff800, v0
	s_nop 1
	v_addc_co_u32_e32 v35, vcc, -1, v1, vcc
	flat_load_dwordx4 v[34:37], v[34:35] nt
	v_add_co_u32_e32 v42, vcc, 0xf77ff800, v0
	s_nop 1
	v_addc_co_u32_e32 v43, vcc, -1, v1, vcc
	flat_load_dwordx4 v[38:41], v[42:43]
	s_cmpk_gt_i32 s3, 0x43ff
	s_waitcnt vmcnt(0) lgkmcnt(0)
	v_and_b32_e32 v3, 0xffff0000, v19
	v_lshlrev_b32_e32 v2, 16, v19
	v_and_b32_e32 v9, 0xffff0000, v18
	v_lshlrev_b32_e32 v8, 16, v18
	v_and_b32_e32 v13, 0xffff0000, v17
	v_lshlrev_b32_e32 v12, 16, v17
	v_and_b32_e32 v17, 0xffff0000, v16
	v_lshlrev_b32_e32 v16, 16, v16
	v_and_b32_e32 v15, 0xffff0000, v21
	v_lshlrev_b32_e32 v14, 16, v21
	v_and_b32_e32 v19, 0xffff0000, v20
	v_lshlrev_b32_e32 v18, 16, v20
	v_and_b32_e32 v21, 0xffff0000, v30
	v_lshlrev_b32_e32 v20, 16, v30
	v_pk_add_f32 v[12:13], v[12:13], v[14:15]
	v_and_b32_e32 v15, 0xffff0000, v31
	v_lshlrev_b32_e32 v14, 16, v31
	s_movk_i32 s6, 0xf800
	v_and_b32_e32 v11, 0xffff0000, v22
	v_lshlrev_b32_e32 v10, 16, v22
	v_pk_add_f32 v[8:9], v[8:9], v[10:11]
	v_and_b32_e32 v11, 0xffff0000, v32
	v_lshlrev_b32_e32 v10, 16, v32
	v_pk_add_f32 v[18:19], v[16:17], v[18:19]
	v_and_b32_e32 v17, 0xffff0000, v33
	v_lshlrev_b32_e32 v16, 16, v33
	s_mov_b32 s6, 0xf77ff800
	v_mov_b32_e32 v59, v19
	s_nop 0
	v_mov_b32_e32 v57, v18
	v_and_b32_e32 v7, 0xffff0000, v23
	v_lshlrev_b32_e32 v6, 16, v23
	v_pk_mul_f32 v[22:23], v[8:9], v[8:9]
	v_mov_b32_e32 v55, v13
	v_pk_add_f32 v[6:7], v[2:3], v[6:7]
	s_mov_b32 s6, 0x358637bd
	v_pk_mul_f32 v[2:3], v[6:7], v[6:7]
	s_waitcnt vmcnt(0) lgkmcnt(0)
	v_and_b32_e32 v51, 0xffff0000, v63
	v_lshlrev_b32_e32 v50, 16, v63
	v_and_b32_e32 v53, 0xffff0000, v35
	v_lshlrev_b32_e32 v52, 16, v35
	v_and_b32_e32 v31, 0xffff0000, v62
	v_lshlrev_b32_e32 v30, 16, v62
	v_and_b32_e32 v35, 0xffff0000, v34
	v_lshlrev_b32_e32 v34, 16, v34
	v_pk_add_f32 v[30:31], v[30:31], v[34:35]
	v_and_b32_e32 v45, 0xffff0000, v65
	v_mov_b32_e32 v58, v31
	v_lshlrev_b32_e32 v44, 16, v65
	v_and_b32_e32 v47, 0xffff0000, v37
	v_lshlrev_b32_e32 v46, 16, v37
	v_and_b32_e32 v33, 0xffff0000, v64
	v_lshlrev_b32_e32 v32, 16, v64
	v_and_b32_e32 v37, 0xffff0000, v36
	v_lshlrev_b32_e32 v36, 16, v36
	v_pk_add_f32 v[50:51], v[50:51], v[52:53]
	v_mov_b32_e32 v56, v30
	v_pk_mul_f32 v[58:59], v[58:59], v[58:59]
	v_pk_add_f32 v[32:33], v[32:33], v[36:37]
	v_and_b32_e32 v53, 0xffff0000, v39
	v_lshlrev_b32_e32 v52, 16, v39
	v_and_b32_e32 v35, 0xffff0000, v38
	v_lshlrev_b32_e32 v34, 16, v38
	v_mov_b32_e32 v38, v50
	v_mov_b32_e32 v39, v12
	v_pk_fma_f32 v[56:57], v[56:57], v[56:57], v[58:59]
	v_pk_mul_f32 v[36:37], v[32:33], v[32:33]
	v_mov_b32_e32 v54, v51
	v_pk_fma_f32 v[38:39], v[38:39], v[38:39], v[56:57]
	v_pk_add_f32 v[44:45], v[44:45], v[46:47]
	v_pk_fma_f32 v[38:39], v[54:55], v[54:55], v[38:39]
	v_mov_b32_e32 v54, v36
	v_mov_b32_e32 v55, v22
	v_pk_mul_f32 v[46:47], v[44:45], v[44:45]
	v_pk_add_f32 v[38:39], v[38:39], v[54:55]
	v_mov_b32_e32 v22, v37
	v_pk_add_f32 v[22:23], v[38:39], v[22:23]
	v_mov_b32_e32 v36, v46
	v_mov_b32_e32 v37, v2
	v_pk_add_f32 v[22:23], v[22:23], v[36:37]
	v_mov_b32_e32 v2, v47
	v_pk_add_f32 v[2:3], v[22:23], v[2:3]
	ds_bpermute_b32 v23, v24, v3
	ds_bpermute_b32 v22, v24, v2
	v_and_b32_e32 v49, 0xffff0000, v40
	v_lshlrev_b32_e32 v48, 16, v40
	s_waitcnt lgkmcnt(0)
	v_pk_add_f32 v[2:3], v[2:3], v[22:23]
	ds_bpermute_b32 v23, v25, v3
	ds_bpermute_b32 v22, v25, v2
	s_waitcnt lgkmcnt(0)
	v_pk_add_f32 v[2:3], v[2:3], v[22:23]
	ds_bpermute_b32 v23, v26, v3
	ds_bpermute_b32 v22, v26, v2
	s_waitcnt lgkmcnt(0)
	v_pk_add_f32 v[2:3], v[2:3], v[22:23]
	ds_bpermute_b32 v23, v27, v3
	ds_bpermute_b32 v22, v27, v2
	s_waitcnt lgkmcnt(0)
	v_pk_add_f32 v[2:3], v[2:3], v[22:23]
	ds_bpermute_b32 v23, v28, v3
	ds_bpermute_b32 v22, v28, v2
	s_waitcnt lgkmcnt(0)
	v_pk_add_f32 v[2:3], v[2:3], v[22:23]
	ds_bpermute_b32 v23, v29, v3
	ds_bpermute_b32 v22, v29, v2
	s_waitcnt lgkmcnt(0)
; __device__ __forceinline__ float bf2f(bf16_t v) { return __uint_as_float((unsigned)v << 16); }
; __device__ __forceinline__ u32x4 pack8(const float* v) { u32x4 w; w.x = cvt_pk_bf16(v[0], v[1]); w.y = cvt_pk_bf16(v[2], v[3]); w.z = cvt_pk_bf16(v[4], v[5]); w.w = cvt_pk_bf16(v[6], v[7]); return w; }
; __global__ void __launch_bounds__(512) mk_fwd(Params P) {
;     ...
;                 for (int hh = 0; hh < 4; ++hh) { const size_t off = (size_t)row * 2048 + hh * 512 + lane * 8;
;                     const bf16x8 a = __builtin_nontemporal_load((const bf16x8*)(OF + off)), b = __builtin_nontemporal_load((const bf16x8*)(OB + off)), gt = *(const bf16x8*)(Gb + off);
;                     float o[8]; float s = 0.f;
; #pragma unroll
;                     for (int e = 0; e < 8; ++e) { o[e] = bf2f((bf16_t)a[e]) + bf2f((bf16_t)b[e]); s += o[e] * o[e]; }
;                     const float rinv = rsqrtf(wave_sum(s) * (1.f / 512.f) + EPS);
; #pragma unroll
;                     for (int e = 0; e < 8; ++e) o[e] = o[e] * rinv * bf2f((bf16_t)gt[e]);
;                     *(u32x4*)(Gb + off) = pack8(o); }
	v_pk_add_f32 v[22:23], v[2:3], v[22:23]
	v_mov_b64_e32 v[2:3], s[6:7]
	v_pk_fma_f32 v[22:23], v[22:23], s[24:25], v[2:3] op_sel_hi:[1,0,0]
	s_nop 0
	v_mul_f32_e32 v36, 0x4b800000, v23
	v_cmp_gt_f32_e64 s[6:7], s53, v23
	v_cmp_gt_f32_e32 vcc, s53, v22
	s_nop 0
	v_cndmask_b32_e64 v23, v23, v36, s[6:7]
	v_rsq_f32_e32 v23, v23
	s_nop 0
	v_mul_f32_e32 v36, 0x45800000, v23
	v_cndmask_b32_e64 v36, v23, v36, s[6:7]
	v_pk_mul_f32 v[18:19], v[36:37], v[18:19] op_sel_hi:[0,1]
	v_pk_mul_f32 v[12:13], v[36:37], v[12:13] op_sel_hi:[0,1]
	v_pk_mul_f32 v[8:9], v[36:37], v[8:9] op_sel_hi:[0,1]
	v_pk_mul_f32 v[6:7], v[36:37], v[6:7] op_sel_hi:[0,1]
	v_pk_mul_f32 v[18:19], v[18:19], v[20:21]
	v_pk_mul_f32 v[12:13], v[12:13], v[14:15]
	v_pk_mul_f32 v[8:9], v[8:9], v[10:11]
	v_pk_mul_f32 v[10:11], v[6:7], v[16:17]
	v_cvt_pk_bf16_f32 v6, v18, v19
	v_cvt_pk_bf16_f32 v7, v12, v13
	v_cvt_pk_bf16_f32 v8, v8, v9
	v_cvt_pk_bf16_f32 v9, v10, v11
	flat_store_dwordx4 v[4:5], v[6:9]
	v_mul_f32_e32 v4, 0x4b800000, v22
	v_cndmask_b32_e32 v4, v22, v4, vcc
	v_rsq_f32_e32 v4, v4
	v_and_b32_e32 v13, 0xffff0000, v41
	v_lshlrev_b32_e32 v12, 16, v41
	s_mov_b32 s6, 0xfbbffc00
	v_mul_f32_e32 v5, 0x45800000, v4
	v_cndmask_b32_e32 v4, v4, v5, vcc
	v_pk_mul_f32 v[6:7], v[4:5], v[30:31] op_sel_hi:[0,1]
	v_pk_mul_f32 v[8:9], v[4:5], v[50:51] op_sel_hi:[0,1]
	v_pk_mul_f32 v[10:11], v[4:5], v[32:33] op_sel_hi:[0,1]
	v_pk_mul_f32 v[4:5], v[4:5], v[44:45] op_sel_hi:[0,1]
	v_pk_mul_f32 v[6:7], v[6:7], v[34:35]
	v_pk_mul_f32 v[8:9], v[8:9], v[52:53]
	v_pk_mul_f32 v[10:11], v[10:11], v[48:49]
	v_pk_mul_f32 v[12:13], v[4:5], v[12:13]
	v_cvt_pk_bf16_f32 v4, v6, v7
	v_cvt_pk_bf16_f32 v5, v8, v9
	v_cvt_pk_bf16_f32 v6, v10, v11
	v_cvt_pk_bf16_f32 v7, v12, v13
	flat_store_dwordx4 v[42:43], v[4:7]
	s_nop 1
	v_add_co_u32_e32 v4, vcc, s6, v0
	s_movk_i32 s6, 0xfc00
	s_nop 0
	v_addc_co_u32_e32 v5, vcc, -1, v1, vcc
	flat_load_dwordx4 v[16:19], v[4:5] nt
	v_add_co_u32_e32 v4, vcc, s6, v0
	s_mov_b32 s6, 0xf77ffc00
	s_nop 0
	v_addc_co_u32_e32 v5, vcc, -1, v1, vcc
	flat_load_dwordx4 v[30:33], v[4:5] nt
	v_add_co_u32_e32 v4, vcc, s6, v0
	s_mov_b32 s6, 0xfbc00000
	s_nop 0
	v_addc_co_u32_e32 v5, vcc, -1, v1, vcc
	flat_load_dwordx4 v[34:37], v[4:5]
	v_add_co_u32_e32 v66, vcc, 0xfbc00000, v0
	s_nop 1
	v_addc_co_u32_e32 v67, vcc, -1, v1, vcc
	flat_load_dwordx4 v[62:65], v[66:67] nt
	flat_load_dwordx4 v[68:71], v[0:1] nt
	v_add_co_u32_e32 v44, vcc, 0xf7800000, v0
	s_nop 1
	v_addc_co_u32_e32 v45, vcc, -1, v1, vcc
	flat_load_dwordx4 v[38:41], v[44:45]
	s_waitcnt vmcnt(0) lgkmcnt(0)
	v_and_b32_e32 v7, 0xffff0000, v19
	v_lshlrev_b32_e32 v6, 16, v19
	v_and_b32_e32 v13, 0xffff0000, v17
	v_lshlrev_b32_e32 v12, 16, v17
	v_and_b32_e32 v17, 0xffff0000, v16
	v_lshlrev_b32_e32 v16, 16, v16
	v_and_b32_e32 v9, 0xffff0000, v33
	v_lshlrev_b32_e32 v8, 16, v33
	v_pk_add_f32 v[6:7], v[6:7], v[8:9]
	v_and_b32_e32 v9, 0xffff0000, v18
	v_lshlrev_b32_e32 v8, 16, v18
	v_and_b32_e32 v19, 0xffff0000, v30
	v_lshlrev_b32_e32 v18, 16, v30
	v_and_b32_e32 v11, 0xffff0000, v32
	v_lshlrev_b32_e32 v10, 16, v32
	v_and_b32_e32 v15, 0xffff0000, v31
	v_lshlrev_b32_e32 v14, 16, v31
	v_pk_add_f32 v[8:9], v[8:9], v[10:11]
	v_and_b32_e32 v11, 0xffff0000, v36
	v_lshlrev_b32_e32 v10, 16, v36
	v_pk_add_f32 v[12:13], v[12:13], v[14:15]
	v_and_b32_e32 v15, 0xffff0000, v35
	v_lshlrev_b32_e32 v14, 16, v35
	v_pk_add_f32 v[18:19], v[16:17], v[18:19]
	v_and_b32_e32 v21, 0xffff0000, v34
	v_lshlrev_b32_e32 v20, 16, v34
	v_and_b32_e32 v17, 0xffff0000, v37
	v_lshlrev_b32_e32 v16, 16, v37
	s_nop 0
	s_mov_b32 s6, 0xf7800000
	v_mov_b32_e32 v61, v19
	s_nop 0
	v_mov_b32_e32 v59, v18
	v_pk_mul_f32 v[42:43], v[8:9], v[8:9]
	v_mov_b32_e32 v57, v13
	v_pk_mul_f32 v[22:23], v[6:7], v[6:7]
	v_lshl_add_u64 v[0:1], v[0:1], 0, s[8:9]
	s_waitcnt vmcnt(0) lgkmcnt(0)
; __device__ __forceinline__ float bf2f(bf16_t v) { return __uint_as_float((unsigned)v << 16); }
; __device__ __forceinline__ u32x4 pack8(const float* v) { u32x4 w; w.x = cvt_pk_bf16(v[0], v[1]); w.y = cvt_pk_bf16(v[2], v[3]); w.z = cvt_pk_bf16(v[4], v[5]); w.w = cvt_pk_bf16(v[6], v[7]); return w; }
; __global__ void __launch_bounds__(512) mk_fwd(Params P) {
;     ...
;                 for (int hh = 0; hh < 4; ++hh) { const size_t off = (size_t)row * 2048 + hh * 512 + lane * 8;
;                     const bf16x8 a = __builtin_nontemporal_load((const bf16x8*)(OF + off)), b = __builtin_nontemporal_load((const bf16x8*)(OB + off)), gt = *(const bf16x8*)(Gb + off);
;                     float o[8]; float s = 0.f;
; #pragma unroll
;                     for (int e = 0; e < 8; ++e) { o[e] = bf2f((bf16_t)a[e]) + bf2f((bf16_t)b[e]); s += o[e] * o[e]; }
;                     const float rinv = rsqrtf(wave_sum(s) * (1.f / 512.f) + EPS);
; #pragma unroll
;                     for (int e = 0; e < 8; ++e) o[e] = o[e] * rinv * bf2f((bf16_t)gt[e]);
;                     *(u32x4*)(Gb + off) = pack8(o); }
	v_and_b32_e32 v53, 0xffff0000, v63
	v_lshlrev_b32_e32 v52, 16, v63
	v_and_b32_e32 v55, 0xffff0000, v69
	v_lshlrev_b32_e32 v54, 16, v69
	v_and_b32_e32 v31, 0xffff0000, v62
	v_lshlrev_b32_e32 v30, 16, v62
	v_and_b32_e32 v35, 0xffff0000, v68
	v_lshlrev_b32_e32 v34, 16, v68
	v_pk_add_f32 v[30:31], v[30:31], v[34:35]
	v_and_b32_e32 v47, 0xffff0000, v65
	v_mov_b32_e32 v60, v31
	v_lshlrev_b32_e32 v46, 16, v65
	v_and_b32_e32 v49, 0xffff0000, v71
	v_lshlrev_b32_e32 v48, 16, v71
	v_and_b32_e32 v33, 0xffff0000, v64
	v_lshlrev_b32_e32 v32, 16, v64
	v_and_b32_e32 v37, 0xffff0000, v70
	v_lshlrev_b32_e32 v36, 16, v70
	v_pk_add_f32 v[52:53], v[52:53], v[54:55]
	v_mov_b32_e32 v58, v30
	v_pk_mul_f32 v[60:61], v[60:61], v[60:61]
	v_pk_add_f32 v[32:33], v[32:33], v[36:37]
	v_and_b32_e32 v55, 0xffff0000, v39
	v_lshlrev_b32_e32 v54, 16, v39
	v_and_b32_e32 v35, 0xffff0000, v38
	v_lshlrev_b32_e32 v34, 16, v38
	v_mov_b32_e32 v38, v52
	v_mov_b32_e32 v39, v12
	v_pk_fma_f32 v[58:59], v[58:59], v[58:59], v[60:61]
	v_pk_mul_f32 v[36:37], v[32:33], v[32:33]
	v_mov_b32_e32 v56, v53
	v_pk_fma_f32 v[38:39], v[38:39], v[38:39], v[58:59]
	v_pk_add_f32 v[46:47], v[46:47], v[48:49]
	v_pk_fma_f32 v[38:39], v[56:57], v[56:57], v[38:39]
	v_mov_b32_e32 v56, v36
	v_mov_b32_e32 v57, v42
	v_pk_mul_f32 v[48:49], v[46:47], v[46:47]
	v_pk_add_f32 v[38:39], v[38:39], v[56:57]
	v_mov_b32_e32 v42, v37
	v_pk_add_f32 v[36:37], v[38:39], v[42:43]
	v_mov_b32_e32 v38, v48
	v_mov_b32_e32 v39, v22
	v_pk_add_f32 v[36:37], v[36:37], v[38:39]
	v_mov_b32_e32 v22, v49
	v_pk_add_f32 v[22:23], v[36:37], v[22:23]
	ds_bpermute_b32 v37, v24, v23
	ds_bpermute_b32 v36, v24, v22
	v_and_b32_e32 v51, 0xffff0000, v40
	v_lshlrev_b32_e32 v50, 16, v40
	s_waitcnt lgkmcnt(0)
	v_pk_add_f32 v[22:23], v[22:23], v[36:37]
	ds_bpermute_b32 v37, v25, v23
	ds_bpermute_b32 v36, v25, v22
	s_waitcnt lgkmcnt(0)
	v_pk_add_f32 v[22:23], v[22:23], v[36:37]
	ds_bpermute_b32 v37, v26, v23
	ds_bpermute_b32 v36, v26, v22
	s_waitcnt lgkmcnt(0)
	v_pk_add_f32 v[22:23], v[22:23], v[36:37]
	ds_bpermute_b32 v37, v27, v23
	ds_bpermute_b32 v36, v27, v22
	s_waitcnt lgkmcnt(0)
	v_pk_add_f32 v[22:23], v[22:23], v[36:37]
	ds_bpermute_b32 v37, v28, v23
	ds_bpermute_b32 v36, v28, v22
	s_waitcnt lgkmcnt(0)
	v_pk_add_f32 v[22:23], v[22:23], v[36:37]
	ds_bpermute_b32 v37, v29, v23
	ds_bpermute_b32 v36, v29, v22
	s_waitcnt lgkmcnt(0)
	v_pk_add_f32 v[22:23], v[22:23], v[36:37]
	s_nop 0
	v_pk_fma_f32 v[2:3], v[22:23], s[24:25], v[2:3] op_sel_hi:[1,0,0]
	s_nop 0
	v_mul_f32_e32 v22, 0x4b800000, v3
	v_cmp_gt_f32_e64 s[6:7], s53, v3
	v_cmp_gt_f32_e32 vcc, s53, v2
	s_nop 0
	v_cndmask_b32_e64 v3, v3, v22, s[6:7]
	v_rsq_f32_e32 v3, v3
	s_nop 0
	v_mul_f32_e32 v22, 0x45800000, v3
	v_cndmask_b32_e64 v22, v3, v22, s[6:7]
	v_mul_f32_e32 v3, 0x4b800000, v2
	v_cndmask_b32_e32 v2, v2, v3, vcc
	v_rsq_f32_e32 v2, v2
	v_pk_mul_f32 v[18:19], v[22:23], v[18:19] op_sel_hi:[0,1]
	v_pk_mul_f32 v[12:13], v[22:23], v[12:13] op_sel_hi:[0,1]
	v_pk_mul_f32 v[8:9], v[22:23], v[8:9] op_sel_hi:[0,1]
	v_pk_mul_f32 v[6:7], v[22:23], v[6:7] op_sel_hi:[0,1]
	v_pk_mul_f32 v[18:19], v[18:19], v[20:21]
	v_pk_mul_f32 v[12:13], v[12:13], v[14:15]
	v_pk_mul_f32 v[8:9], v[8:9], v[10:11]
	v_pk_mul_f32 v[10:11], v[6:7], v[16:17]
	v_mul_f32_e32 v3, 0x45800000, v2
	v_cvt_pk_bf16_f32 v6, v18, v19
	v_cvt_pk_bf16_f32 v7, v12, v13
	v_cvt_pk_bf16_f32 v8, v8, v9
	v_cvt_pk_bf16_f32 v9, v10, v11
	v_cndmask_b32_e32 v2, v2, v3, vcc
	flat_store_dwordx4 v[4:5], v[6:9]
	v_pk_mul_f32 v[4:5], v[2:3], v[30:31] op_sel_hi:[0,1]
	v_and_b32_e32 v11, 0xffff0000, v41
	v_pk_mul_f32 v[6:7], v[2:3], v[52:53] op_sel_hi:[0,1]
	v_pk_mul_f32 v[8:9], v[2:3], v[32:33] op_sel_hi:[0,1]
	v_pk_mul_f32 v[2:3], v[2:3], v[46:47] op_sel_hi:[0,1]
	v_lshlrev_b32_e32 v10, 16, v41
	v_pk_mul_f32 v[4:5], v[4:5], v[34:35]
	v_pk_mul_f32 v[6:7], v[6:7], v[54:55]
	v_pk_mul_f32 v[8:9], v[8:9], v[50:51]
	v_pk_mul_f32 v[10:11], v[2:3], v[10:11]
	v_cvt_pk_bf16_f32 v2, v4, v5
	v_cvt_pk_bf16_f32 v3, v6, v7
	v_cvt_pk_bf16_f32 v4, v8, v9
	v_cvt_pk_bf16_f32 v5, v10, v11
	flat_store_dwordx4 v[44:45], v[2:5]
	s_cbranch_scc0 .LBB0_63
